# speedup vs baseline: 1.0088x; 1.0088x over previous
; #define MFMA(a, b, c) __builtin_amdgcn_mfma_f32_16x16x32_bf16(a, b, c, 0, 0, 0)
; template <class Epi>
; __device__ __forceinline__ void gemm_phase(const u16* __restrict__ A, int lda, const u16* __restrict__ Bt, int ldb, int K,
;                                            int MT, int NT, bool lat_only, char* smem, Epi epi) {
;     ...
;       const char* sa = smem + stg * 49152;
;       const char* sb = sa + 32768;
; #pragma unroll
;       for (int ks = 0; ks < 2; ++ks) {
;         bf16x8 af[4], bf[4];
; #pragma unroll
;         for (int m = 0; m < 4; ++m) af[m] = *(const bf16x8*)(sa + sw128(wr * 64 + m * 16 + fr, ks * 4 + fq));
; #pragma unroll
;         for (int n = 0; n < 4; ++n) bf[n] = *(const bf16x8*)(sb + sw128(wc * 64 + n * 16 + fr, ks * 4 + fq));
;         __builtin_amdgcn_s_setprio(1);
; #pragma unroll
;         for (int m = 0; m < 4; ++m)
; #pragma unroll
;           for (int n = 0; n < 4; ++n) acc[m][n] = MFMA(bf[n], af[m], acc[m][n]);
;         __builtin_amdgcn_s_setprio(0);
.LBB0_401:
	s_or_b64 exec, exec, s[14:15]
	s_mul_i32 s14, s2, 0xc000
	s_addk_i32 s14, 0x190
	v_add_u32_e32 v133, s14, v129
	v_add_u32_e32 v146, v133, v128
	v_add3_u32 v162, s14, v128, v130
	ds_read_b128 v[134:137], v146
	ds_read_b128 v[138:141], v146 offset:2048
	ds_read_b128 v[142:145], v146 offset:4096
	ds_read_b128 v[146:149], v146 offset:6144
	ds_read_b128 v[150:153], v162 offset:32768
	ds_read_b128 v[154:157], v162 offset:34816
	ds_read_b128 v[158:161], v162 offset:36864
	ds_read_b128 v[162:165], v162 offset:38912
	s_cmp_lg_u32 s0, 0
	s_cbranch_scc1 .Lsq399_1
	s_setprio 1
.Lsq399_1:
	s_waitcnt lgkmcnt(0)
	v_mfma_f32_16x16x32_bf16 v[60:63], v[150:153], v[134:137], v[60:63]
	v_mfma_f32_16x16x32_bf16 v[56:59], v[154:157], v[134:137], v[56:59]
	v_mfma_f32_16x16x32_bf16 v[52:55], v[158:161], v[134:137], v[52:55]
	v_mfma_f32_16x16x32_bf16 v[48:51], v[162:165], v[134:137], v[48:51]
	v_mfma_f32_16x16x32_bf16 v[44:47], v[150:153], v[138:141], v[44:47]
	v_mfma_f32_16x16x32_bf16 v[40:43], v[154:157], v[138:141], v[40:43]
	v_mfma_f32_16x16x32_bf16 v[36:39], v[158:161], v[138:141], v[36:39]
	v_mfma_f32_16x16x32_bf16 v[32:35], v[162:165], v[138:141], v[32:35]
	v_mfma_f32_16x16x32_bf16 v[28:31], v[150:153], v[142:145], v[28:31]
	v_mfma_f32_16x16x32_bf16 v[24:27], v[154:157], v[142:145], v[24:27]
	v_mfma_f32_16x16x32_bf16 v[20:23], v[158:161], v[142:145], v[20:23]
	v_mfma_f32_16x16x32_bf16 v[16:19], v[162:165], v[142:145], v[16:19]
	v_mfma_f32_16x16x32_bf16 v[12:15], v[150:153], v[146:149], v[12:15]
	v_mfma_f32_16x16x32_bf16 v[8:11], v[154:157], v[146:149], v[8:11]
	v_mfma_f32_16x16x32_bf16 v[4:7], v[158:161], v[146:149], v[4:7]
	v_mfma_f32_16x16x32_bf16 v[0:3], v[162:165], v[146:149], v[0:3]
	s_cmp_lg_u32 s0, 0
	s_cbranch_scc0 .Lsp399_1
	s_setprio 0
.Lsp399_1:
	v_add_u32_e32 v150, s14, v131
	v_add_u32_e32 v134, v150, v129
	v_add_u32_e32 v133, v133, v131
	ds_read_b128 v[134:137], v134
	ds_read_b128 v[138:141], v133 offset:2048
	ds_read_b128 v[142:145], v133 offset:4096
	ds_read_b128 v[146:149], v133 offset:6144
	v_add_u32_e32 v133, v150, v130
	ds_read_b128 v[150:153], v133 offset:32768
	ds_read_b128 v[154:157], v133 offset:34816
	ds_read_b128 v[158:161], v133 offset:36864
	ds_read_b128 v[162:165], v133 offset:38912
	s_cmp_lg_u32 s0, 0
	s_cbranch_scc1 .Lsq399_0
	s_setprio 1

; template <class Epi>
; __device__ __forceinline__ void gemm_phase(const u16* __restrict__ A, int lda, const u16* __restrict__ Bt, int ldb, int K,
;                                            int MT, int NT, bool lat_only, char* smem, Epi epi) {
;     ...
;       if (late && kt + 2 < nk) GSTAGE(stg2, kt + 2);
;       if (kt + 2 < nk) asm volatile("s_waitcnt vmcnt(6)" ::: "memory");
;       else asm volatile("s_waitcnt vmcnt(0)" ::: "memory");
.Lsp399_0:
	s_cmp_lt_u32 s5, 14
	s_cselect_b64 s[14:15], -1, 0
	s_and_b64 s[86:87], s[6:7], s[14:15]
	s_and_saveexec_b64 s[14:15], s[86:87]
	s_cbranch_execnz .LBB0_404
	s_or_b64 exec, exec, s[14:15]
	s_mov_b64 s[14:15], -1
	s_and_b64 vcc, exec, s[12:13]
	s_cbranch_vccnz .LBB0_405

; template <class Epi>
; __device__ __forceinline__ void gemm_phase(const u16* __restrict__ A, int lda, const u16* __restrict__ Bt, int ldb, int K,
;                                            int MT, int NT, bool lat_only, char* smem, Epi epi) {
;     ...
;       const char* sa = smem + stg * 49152;
;       const char* sb = sa + 32768;
; #pragma unroll
;       for (int ks = 0; ks < 2; ++ks) {
;         bf16x8 af[4], bf[4];
; #pragma unroll
;         for (int m = 0; m < 4; ++m) af[m] = *(const bf16x8*)(sa + sw128(wr * 64 + m * 16 + fr, ks * 4 + fq));
; #pragma unroll
;         for (int n = 0; n < 4; ++n) bf[n] = *(const bf16x8*)(sb + sw128(wc * 64 + n * 16 + fr, ks * 4 + fq));
;         __builtin_amdgcn_s_setprio(1);
.LBB0_445:
	s_or_b64 exec, exec, s[14:15]
	s_mul_i32 s14, s7, 0xc000
	s_addk_i32 s14, 0x190
	v_add_u32_e32 v133, s14, v128
	v_add_u32_e32 v146, v133, v129
	v_add_u32_e32 v133, v133, v130
	ds_read_b128 v[134:137], v146
	ds_read_b128 v[138:141], v146 offset:2048
	ds_read_b128 v[142:145], v146 offset:4096
	ds_read_b128 v[146:149], v146 offset:6144
	ds_read_b128 v[150:153], v133 offset:32768
	ds_read_b128 v[154:157], v133 offset:34816
	ds_read_b128 v[158:161], v133 offset:36864
	ds_read_b128 v[162:165], v133 offset:38912
	s_cmp_lg_u32 s0, 0
	s_cbranch_scc1 .Lsq443_1
	s_setprio 1

; template <class Epi>
; __device__ __forceinline__ void gemm_phase(const u16* __restrict__ A, int lda, const u16* __restrict__ Bt, int ldb, int K,
;                                            int MT, int NT, bool lat_only, char* smem, Epi epi) {
;     ...
;         bf16x8 af[4], bf[4];
; #pragma unroll
;         for (int m = 0; m < 4; ++m) af[m] = *(const bf16x8*)(sa + sw128(wr * 64 + m * 16 + fr, ks * 4 + fq));
; #pragma unroll
;         for (int n = 0; n < 4; ++n) bf[n] = *(const bf16x8*)(sb + sw128(wc * 64 + n * 16 + fr, ks * 4 + fq));
;         __builtin_amdgcn_s_setprio(1);
.Lsp443_1:
	v_add_u32_e32 v133, s14, v131
	v_add_u32_e32 v146, v133, v129
	v_add_u32_e32 v133, v133, v130
	ds_read_b128 v[134:137], v146
	ds_read_b128 v[138:141], v146 offset:2048
	ds_read_b128 v[142:145], v146 offset:4096
	ds_read_b128 v[146:149], v146 offset:6144
	ds_read_b128 v[150:153], v133 offset:32768
	ds_read_b128 v[154:157], v133 offset:34816
	ds_read_b128 v[158:161], v133 offset:36864
	ds_read_b128 v[162:165], v133 offset:38912
	s_cmp_lg_u32 s0, 0
	s_cbranch_scc1 .Lsq443_0
	s_setprio 1

; template <class Epi>
; __device__ __forceinline__ void gemm_phase(const u16* __restrict__ A, int lda, const u16* __restrict__ Bt, int ldb, int K,
;                                            int MT, int NT, bool lat_only, char* smem, Epi epi) {
;     ...
;       if (late && kt + 2 < nk) GSTAGE(stg2, kt + 2);
;       if (kt + 2 < nk) asm volatile("s_waitcnt vmcnt(6)" ::: "memory");
;       else asm volatile("s_waitcnt vmcnt(0)" ::: "memory");
.Lsp443_0:
	s_cmp_lt_u32 s9, 14
	s_cselect_b64 s[14:15], -1, 0
	s_and_b64 s[74:75], s[4:5], s[14:15]
	s_and_saveexec_b64 s[14:15], s[74:75]
	s_cbranch_execnz .LBB0_448
	s_or_b64 exec, exec, s[14:15]
	s_mov_b64 s[14:15], -1
	s_and_b64 vcc, exec, s[12:13]
	s_cbranch_vccnz .LBB0_449

; template <class Epi>
; __device__ __forceinline__ void gemm_phase(const u16* __restrict__ A, int lda, const u16* __restrict__ Bt, int ldb, int K,
;                                            int MT, int NT, bool lat_only, char* smem, Epi epi) {
;     ...
;       const char* sa = smem + stg * 49152;
;       const char* sb = sa + 32768;
; #pragma unroll
;       for (int ks = 0; ks < 2; ++ks) {
;         bf16x8 af[4], bf[4];
; #pragma unroll
;         for (int m = 0; m < 4; ++m) af[m] = *(const bf16x8*)(sa + sw128(wr * 64 + m * 16 + fr, ks * 4 + fq));
; #pragma unroll
;         for (int n = 0; n < 4; ++n) bf[n] = *(const bf16x8*)(sb + sw128(wc * 64 + n * 16 + fr, ks * 4 + fq));
;         __builtin_amdgcn_s_setprio(1);
.LBB0_472:
	s_or_b64 exec, exec, s[46:47]
	s_mul_i32 s40, s15, 0xc000
	s_addk_i32 s40, 0x190
	v_add_u32_e32 v133, s40, v128
	v_add_u32_e32 v146, v133, v129
	v_add_u32_e32 v133, v133, v130
	ds_read_b128 v[134:137], v146
	ds_read_b128 v[138:141], v146 offset:2048
	ds_read_b128 v[142:145], v146 offset:4096
	ds_read_b128 v[146:149], v146 offset:6144
	ds_read_b128 v[150:153], v133 offset:32768
	ds_read_b128 v[154:157], v133 offset:34816
	ds_read_b128 v[158:161], v133 offset:36864
	ds_read_b128 v[162:165], v133 offset:38912
	s_cmp_lg_u32 s0, 0
	s_cbranch_scc1 .Lsq470_1
	s_setprio 1

; template <class Epi>
; __device__ __forceinline__ void gemm_phase(const u16* __restrict__ A, int lda, const u16* __restrict__ Bt, int ldb, int K,
;                                            int MT, int NT, bool lat_only, char* smem, Epi epi) {
;     ...
;         bf16x8 af[4], bf[4];
; #pragma unroll
;         for (int m = 0; m < 4; ++m) af[m] = *(const bf16x8*)(sa + sw128(wr * 64 + m * 16 + fr, ks * 4 + fq));
; #pragma unroll
;         for (int n = 0; n < 4; ++n) bf[n] = *(const bf16x8*)(sb + sw128(wc * 64 + n * 16 + fr, ks * 4 + fq));
;         __builtin_amdgcn_s_setprio(1);
.Lsp470_1:
	v_add_u32_e32 v133, s40, v131
	v_add_u32_e32 v146, v133, v129
	v_add_u32_e32 v133, v133, v130
	ds_read_b128 v[134:137], v146
	ds_read_b128 v[138:141], v146 offset:2048
	ds_read_b128 v[142:145], v146 offset:4096
	ds_read_b128 v[146:149], v146 offset:6144
	ds_read_b128 v[150:153], v133 offset:32768
	ds_read_b128 v[154:157], v133 offset:34816
	ds_read_b128 v[158:161], v133 offset:36864
	ds_read_b128 v[162:165], v133 offset:38912
	s_cmp_lg_u32 s0, 0
	s_cbranch_scc1 .Lsq470_0
	s_setprio 1

; template <class Epi>
; __device__ __forceinline__ void gemm_phase(const u16* __restrict__ A, int lda, const u16* __restrict__ Bt, int ldb, int K,
;                                            int MT, int NT, bool lat_only, char* smem, Epi epi) {
;     ...
;       if (late && kt + 2 < nk) GSTAGE(stg2, kt + 2);
;       if (kt + 2 < nk) asm volatile("s_waitcnt vmcnt(6)" ::: "memory");
;       else asm volatile("s_waitcnt vmcnt(0)" ::: "memory");
.Lsp470_0:
	s_cmp_lt_u32 s17, 14
	s_cselect_b64 s[46:47], -1, 0
	s_and_b64 s[86:87], s[12:13], s[46:47]
	s_and_saveexec_b64 s[46:47], s[86:87]
	s_cbranch_execnz .LBB0_475
	s_or_b64 exec, exec, s[46:47]
	s_mov_b64 s[46:47], -1
	s_and_b64 vcc, exec, s[44:45]
	s_cbranch_vccnz .LBB0_476

; template <class Epi>
; __device__ __forceinline__ void gemm_phase(const u16* __restrict__ A, int lda, const u16* __restrict__ Bt, int ldb, int K,
;                                            int MT, int NT, bool lat_only, char* smem, Epi epi) {
;     ...
;       if (late && kt + 2 < nk) GSTAGE(stg2, kt + 2);
;       if (kt + 2 < nk) asm volatile("s_waitcnt vmcnt(6)" ::: "memory");
;       else asm volatile("s_waitcnt vmcnt(0)" ::: "memory");
.Lsp916_0:
	s_cmp_lt_u32 s47, 14
	s_cselect_b64 s[14:15], -1, 0
	s_xor_b64 s[50:51], s[0:1], -1
	s_and_b64 s[50:51], s[50:51], s[14:15]
	s_and_saveexec_b64 s[14:15], s[50:51]
	s_cbranch_execnz .LBB0_921
	s_or_b64 exec, exec, s[14:15]
	s_mov_b64 s[14:15], -1
	s_and_b64 vcc, exec, s[12:13]
	s_cbranch_vccnz .LBB0_922
